# mix phase item rebalance: the 128 workgroups that carry an extra context-scan item swap three window-attention items for small context-attention items of other workgroups
# speedup vs baseline: 1.1039x; 1.0131x over previous
.LBB0_645:
	s_add_i32 s54, s62, s85
	s_cmpk_lg_u32 s33, 0x200
	s_cbranch_scc1 .Lmixbal_done
	s_cmpk_lt_u32 s85, 0x80
	s_cbranch_scc0 .Lmixbal_hi
	s_sub_i32 s98, s62, 0xe00
	s_cmpk_gt_u32 s98, 0x400
	s_cbranch_scc1 .Lmixbal_done
	s_lshr_b32 s98, s98, 2
	s_add_i32 s54, s85, 0x1480
	s_add_i32 s54, s54, s98
	s_branch .Lmixbal_done
.Lmixbal_hi:
	s_cmpk_lg_u32 s62, 0x1400
	s_cbranch_scc1 .Lmixbal_done
	s_sub_i32 s98, s85, 0x80
	s_lshr_b32 s99, s98, 7
	s_lshl_b32 s99, s99, 9
	s_and_b32 s98, s98, 0x7f
	s_add_i32 s54, s98, s99
	s_add_i32 s54, s54, 0xe00
.Lmixbal_done:
	s_cmpk_gt_i32 s54, 0x167f
	s_cbranch_scc1 .LBB0_644
	s_cmpk_lt_i32 s54, 0x400
	s_cbranch_scc1 .LBB0_652
	s_cmpk_gt_u32 s54, 0x47f
	s_mov_b64 s[0:1], -1
	s_cbranch_scc0 .LBB0_649
	s_add_i32 s0, s54, 0xffffff80
	s_cmpk_lt_u32 s54, 0x1480
	s_cselect_b32 s2, s0, s54
	s_mov_b64 s[0:1], 0
